# norm loop and outproj epilogue: loads issued together with one wait instead of load/wait ladders; flat->global there
# speedup vs baseline: 1.0010x; 1.0010x over previous
; DEV void phase_outproj(const Params& p, int l, int hf, char* smem) {
;     ...
; #pragma unroll
;     for (int j = 0; j < 2; ++j) {
;       const int m = mt * 256 + wm * 64 + 32 * j + r;
;       const int bl = m / TP, tp = m - bl * TP;
;       const int b = hf * 2 + bl;
;       const int n0 = nt * 128 + wn * 64;
;       const float* src;
;       float* dst;
;       const float* gate;
;       if (tp < CTXL) {
;         src = p.ctx + ((size_t)b * CTXL + tp) * DM;
;         dst = (float*)(ws + OFF_CTX1) + ((size_t)b * CTXL + tp) * DM;
;         gate = mod + 4 * 3072 + 2048;
;       } else {
;         src = xs + ((size_t)b * SEQ + (tp - CTXL)) * DM;
;         dst = p.out + ((size_t)b * SEQ + (tp - CTXL)) * DM;
;         gate = mod + b * 3072 + 2048;
;       }
; #pragma unroll
;       for (int i = 0; i < 2; ++i)
; #pragma unroll
;         for (int g4 = 0; g4 < 4; ++g4) {
;           const int n = n0 + 32 * i + 8 * g4 + 4 * h;
;           const float4 xv = xpre[i][j][g4];
;           const float4 gv = *(const float4*)(gate + n);
;           float4 o;
;           o.x = xv.x + gv.x * acc[i][j][4 * g4];
;           o.y = xv.y + gv.y * acc[i][j][4 * g4 + 1];
;           o.z = xv.z + gv.z * acc[i][j][4 * g4 + 2];
;           o.w = xv.w + gv.w * acc[i][j][4 * g4 + 3];
;           *(float4*)(dst + n) = o;
;         }
.LBB0_18:
	s_or_b64 exec, exec, s[2:3]
	v_lshl_add_u64 v[36:37], v[34:35], 0, v[134:135]
	v_lshl_add_u64 v[38:39], v[32:33], 0, v[134:135]
	global_load_dwordx4 v[228:231], v[36:37], off
	global_load_dwordx4 v[232:235], v[36:37], off offset:32
	global_load_dwordx4 v[236:239], v[36:37], off offset:64
	global_load_dwordx4 v[244:247], v[36:37], off offset:96
	global_load_dwordx4 v[248:251], v[36:37], off offset:128
	global_load_dwordx4 v[252:255], v[36:37], off offset:160
	s_waitcnt vmcnt(0) lgkmcnt(0)
	v_pk_fma_f32 v[16:17], v[16:17], v[228:229], v[92:93]
	v_pk_fma_f32 v[18:19], v[18:19], v[230:231], v[94:95]
	global_store_dwordx4 v[38:39], v[16:19], off
	global_load_dwordx4 v[228:231], v[36:37], off offset:192
	v_pk_fma_f32 v[20:21], v[20:21], v[232:233], v[88:89]
	v_pk_fma_f32 v[22:23], v[22:23], v[234:235], v[90:91]
	global_store_dwordx4 v[38:39], v[20:23], off offset:32
	global_load_dwordx4 v[232:235], v[36:37], off offset:224
	v_pk_fma_f32 v[24:25], v[24:25], v[236:237], v[84:85]
	v_pk_fma_f32 v[26:27], v[26:27], v[238:239], v[86:87]
	global_store_dwordx4 v[38:39], v[24:27], off offset:64
	v_pk_fma_f32 v[28:29], v[28:29], v[244:245], v[80:81]
	v_pk_fma_f32 v[30:31], v[30:31], v[246:247], v[82:83]
	global_store_dwordx4 v[38:39], v[28:31], off offset:96
	v_pk_fma_f32 v[0:1], v[0:1], v[248:249], v[76:77]
	v_pk_fma_f32 v[2:3], v[2:3], v[250:251], v[78:79]
	global_store_dwordx4 v[38:39], v[0:3], off offset:128
	v_pk_fma_f32 v[4:5], v[4:5], v[252:253], v[72:73]
	v_pk_fma_f32 v[6:7], v[6:7], v[254:255], v[74:75]
	global_store_dwordx4 v[38:39], v[4:7], off offset:160
	s_waitcnt vmcnt(4)
	v_pk_fma_f32 v[8:9], v[8:9], v[228:229], v[68:69]
	v_pk_fma_f32 v[10:11], v[10:11], v[230:231], v[70:71]
	global_store_dwordx4 v[38:39], v[8:11], off offset:192
	v_pk_fma_f32 v[12:13], v[12:13], v[232:233], v[64:65]
	v_pk_fma_f32 v[14:15], v[14:15], v[234:235], v[66:67]
	global_store_dwordx4 v[38:39], v[12:15], off offset:224
	s_load_dword s2, s[74:75], 0x0
	s_waitcnt lgkmcnt(0)
	s_add_i32 s20, s2, s20
	s_cmpk_gt_i32 s20, 0x1ff
	s_cbranch_scc1 .LBB0_28

; DEV void phase_outproj(const Params& p, int l, int hf, char* smem) {
;     ...
; #pragma unroll
;     for (int j = 0; j < 2; ++j) {
;       const int m = mt * 256 + wm * 64 + 32 * j + r;
;       const int bl = m / TP, tp = m - bl * TP;
;       const int b = hf * 2 + bl;
;       const int n0 = nt * 128 + wn * 64;
;       const float* src;
;       float* dst;
;       const float* gate;
;       if (tp < CTXL) {
;         src = p.ctx + ((size_t)b * CTXL + tp) * DM;
;         dst = (float*)(ws + OFF_CTX1) + ((size_t)b * CTXL + tp) * DM;
;         gate = mod + 4 * 3072 + 2048;
;       } else {
;         src = xs + ((size_t)b * SEQ + (tp - CTXL)) * DM;
;         dst = p.out + ((size_t)b * SEQ + (tp - CTXL)) * DM;
;         gate = mod + b * 3072 + 2048;
;       }
; #pragma unroll
;       for (int i = 0; i < 2; ++i)
; #pragma unroll
;         for (int g4 = 0; g4 < 4; ++g4) {
;           const int n = n0 + 32 * i + 8 * g4 + 4 * h;
;           const float4 xv = xpre[i][j][g4];
;           const float4 gv = *(const float4*)(gate + n);
;           float4 o;
;           o.x = xv.x + gv.x * acc[i][j][4 * g4];
;           o.y = xv.y + gv.y * acc[i][j][4 * g4 + 1];
;           o.z = xv.z + gv.z * acc[i][j][4 * g4 + 2];
;           o.w = xv.w + gv.w * acc[i][j][4 * g4 + 3];
;           *(float4*)(dst + n) = o;
;         }
.LBB0_21:
	s_andn2_saveexec_b64 s[12:13], s[12:13]
	v_lshlrev_b64 v[134:135], 20, v[134:135]
	v_lshl_add_u64 v[134:135], s[8:9], 0, v[134:135]
	v_lshlrev_b64 v[136:137], 12, v[136:137]
	v_lshl_add_u64 v[138:139], v[134:135], 0, v[136:137]
	v_mov_b64_e32 v[140:141], s[10:11]
	s_or_b64 exec, exec, s[12:13]
	v_or_b32_e32 v134, s2, v151
	v_ashrrev_i32_e32 v135, 31, v134
	v_lshlrev_b64 v[134:135], 2, v[134:135]
	v_lshl_add_u64 v[136:137], v[140:141], 0, v[134:135]
	s_waitcnt vmcnt(0)
	v_lshl_add_u64 v[138:139], v[138:139], 0, v[134:135]
	global_load_dwordx4 v[228:231], v[136:137], off
	global_load_dwordx4 v[232:235], v[136:137], off offset:32
	global_load_dwordx4 v[236:239], v[136:137], off offset:64
	global_load_dwordx4 v[244:247], v[136:137], off offset:96
	global_load_dwordx4 v[248:251], v[136:137], off offset:128
	global_load_dwordx4 v[252:255], v[136:137], off offset:160
	s_waitcnt vmcnt(0) lgkmcnt(0)
	v_pk_fma_f32 v[48:49], v[48:49], v[228:229], v[124:125]
	v_pk_fma_f32 v[50:51], v[50:51], v[230:231], v[126:127]
	global_store_dwordx4 v[138:139], v[48:51], off
	global_load_dwordx4 v[228:231], v[136:137], off offset:192
	v_pk_fma_f32 v[52:53], v[52:53], v[232:233], v[120:121]
	v_pk_fma_f32 v[54:55], v[54:55], v[234:235], v[122:123]
	global_store_dwordx4 v[138:139], v[52:55], off offset:32
	global_load_dwordx4 v[232:235], v[136:137], off offset:224
	v_pk_fma_f32 v[56:57], v[56:57], v[236:237], v[116:117]
	v_pk_fma_f32 v[58:59], v[58:59], v[238:239], v[118:119]
	global_store_dwordx4 v[138:139], v[56:59], off offset:64
	v_pk_fma_f32 v[60:61], v[60:61], v[244:245], v[112:113]
	v_pk_fma_f32 v[62:63], v[62:63], v[246:247], v[114:115]
	global_store_dwordx4 v[138:139], v[60:63], off offset:96
	v_pk_fma_f32 v[32:33], v[32:33], v[248:249], v[108:109]
	v_pk_fma_f32 v[34:35], v[34:35], v[250:251], v[110:111]
	global_store_dwordx4 v[138:139], v[32:35], off offset:128
	v_pk_fma_f32 v[36:37], v[36:37], v[252:253], v[104:105]
	v_pk_fma_f32 v[38:39], v[38:39], v[254:255], v[106:107]
	global_store_dwordx4 v[138:139], v[36:39], off offset:160
	s_waitcnt vmcnt(4)
	v_pk_fma_f32 v[40:41], v[40:41], v[228:229], v[100:101]
	v_pk_fma_f32 v[42:43], v[42:43], v[230:231], v[102:103]
	global_store_dwordx4 v[138:139], v[40:43], off offset:192
	v_or_b32_e32 v36, 32, v154
	v_mul_hi_i32 v37, v36, s72
	v_lshrrev_b32_e32 v38, 31, v37
	v_ashrrev_i32_e32 v37, 11, v37
	v_add_u32_e32 v37, v37, v38
	v_mad_i32_i24 v38, v37, s73, v36
	v_add_u32_e32 v36, s19, v37
	v_cmp_lt_i32_e32 vcc, s70, v38
	v_ashrrev_i32_e32 v37, 31, v36
	v_pk_fma_f32 v[44:45], v[44:45], v[232:233], v[96:97]
	v_pk_fma_f32 v[46:47], v[46:47], v[234:235], v[98:99]
	global_store_dwordx4 v[138:139], v[44:47], off offset:224
	s_and_saveexec_b64 s[2:3], vcc
	v_readlane_b32 s40, v241, 51
	s_xor_b64 s[2:3], exec, s[2:3]
	v_readlane_b32 s41, v241, 52
	v_readlane_b32 s42, v241, 53
	v_readlane_b32 s43, v241, 54
	v_readlane_b32 s44, v241, 55
	v_readlane_b32 s45, v241, 56
	v_readlane_b32 s46, v241, 57
	v_readlane_b32 s47, v241, 58
	v_readlane_b32 s48, v241, 59
	v_readlane_b32 s49, v241, 60
	v_readlane_b32 s50, v241, 61
	v_readlane_b32 s51, v241, 62
	v_readlane_b32 s52, v241, 63
	v_readlane_b32 s53, v240, 0
	v_readlane_b32 s54, v240, 1
	v_readlane_b32 s55, v240, 2
	s_cbranch_execz .LBB0_25
	v_readlane_b32 s24, v242, 1
	v_add_u32_e32 v144, 0xffffff00, v38
	v_lshlrev_b64 v[32:33], 25, v[36:37]
	v_readlane_b32 s28, v242, 5
	v_readlane_b32 s29, v242, 6
	v_lshlrev_b64 v[34:35], 12, v[144:145]
	s_mov_b64 s[12:13], 0x2000
	v_lshl_add_u64 v[32:33], s[28:29], 0, v[32:33]
	v_lshl_add_u64 v[32:33], v[32:33], 0, v[34:35]
	v_mul_i32_i24_e32 v34, 0xc00, v36
	v_ashrrev_i32_e32 v35, 31, v34
	v_lshl_add_u64 v[34:35], v[34:35], 2, s[0:1]
	v_lshl_add_u64 v[34:35], v[34:35], 0, s[12:13]
	v_readlane_b32 s25, v242, 2
	v_readlane_b32 s26, v242, 3
	v_readlane_b32 s27, v242, 4
	v_readlane_b32 s30, v242, 7
	v_readlane_b32 s31, v242, 8

; DEV uint2 pk4(float a, float b, float c, float d) { return make_uint2(pk2(a, b), pk2(c, d)); }
; DEV void phase_norm(const Params& p, int l) {
;     ...
;   for (int m = blockIdx.x * 8 + (tid >> 6); m < MALL; m += gridDim.x * 8) {
;     const int b = m / TP, tp = m - b * TP;
;     const float* src = (tp < CTXL) ? cs + ((size_t)b * CTXL + tp) * DM : xs + ((size_t)b * SEQ + (tp - CTXL)) * DM;
;     const float* md = mod + ((tp < CTXL) ? 4 : b) * 3072;
;     float4 v[4];
;     float ss = 0;
; #pragma unroll
;     for (int i = 0; i < 4; ++i) {
;       v[i] = *(const float4*)(src + i * 256 + lane * 4);
;       ss += v[i].x * v[i].x + v[i].y * v[i].y + v[i].z * v[i].z + v[i].w * v[i].w;
;     }
; #pragma unroll
;     for (int o = 1; o < 64; o <<= 1) ss += __shfl_xor(ss, o, 64);
;     const float rs = rsqrtf(ss * (1.f / 1024.f) + EPS);
; #pragma unroll
;     for (int i = 0; i < 4; ++i) {
;       const int n = i * 256 + lane * 4;
;       const float4 gg = *(const float4*)(g + n);
;       const float4 sh = *(const float4*)(md + n);
;       const float4 sc = *(const float4*)(md + 1024 + n);
;       const float o0 = v[i].x * rs * gg.x * (1.f + sc.x) + sh.x;
;       const float o1 = v[i].y * rs * gg.y * (1.f + sc.y) + sh.y;
;       const float o2 = v[i].z * rs * gg.z * (1.f + sc.z) + sh.z;
;       const float o3 = v[i].w * rs * gg.w * (1.f + sc.w) + sh.w;
;       *(uint2*)(H + (size_t)(m >> 8) * (256 * 1024) + (size_t)(n >> 6) * (256 * 64) + (m & 255) * 64 + (n & 63)) = pk4(o0, o1, o2, o3);
;     }
.LBB0_493:
	s_or_b64 exec, exec, s[12:13]
	v_lshl_add_u64 v[24:25], v[20:21], 0, v[144:145]
	global_load_dwordx4 v[20:23], v[24:25], off
	global_load_dwordx4 v[34:37], v[24:25], off offset:1024
	global_load_dwordx4 v[38:41], v[24:25], off offset:2048
	global_load_dwordx4 v[42:45], v[24:25], off offset:3072
	v_lshl_add_u64 v[18:19], v[18:19], 2, s[6:7]
	s_mov_b64 s[12:13], 0x1000
	v_lshl_add_u64 v[58:59], v[18:19], 0, s[12:13]
	v_lshl_add_u64 v[24:25], v[58:59], 0, v[144:145]
	global_load_dwordx4 v[46:49], v[24:25], off
	global_load_dwordx4 v[78:81], v[24:25], off offset:1024
	global_load_dwordx4 v[90:93], v[24:25], off offset:2048
	global_load_dwordx4 v[102:105], v[24:25], off offset:3072
	global_load_dwordx4 v[50:53], v[0:1], off
	global_load_dwordx4 v[74:77], v[0:1], off offset:1024
	global_load_dwordx4 v[86:89], v[0:1], off offset:2048
	global_load_dwordx4 v[98:101], v[0:1], off offset:3072
	v_lshl_add_u64 v[60:61], v[18:19], 0, v[144:145]
	global_load_dwordx4 v[54:57], v[60:61], off
	global_load_dwordx4 v[82:85], v[60:61], off offset:1024
	global_load_dwordx4 v[94:97], v[60:61], off offset:2048
	global_load_dwordx4 v[106:109], v[60:61], off offset:3072
	v_and_b32_e32 v11, 0x3fc0, v33
	v_mov_b32_e32 v15, v145
	s_mov_b32 s12, 0x83ff
	v_mov_b32_e32 v17, v145
	v_add_u32_e32 v33, s15, v33
	s_waitcnt vmcnt(0) lgkmcnt(0)
	v_mov_b32_e32 v24, v21
	v_mov_b32_e32 v25, v35
	v_mov_b32_e32 v18, v20
	v_mov_b32_e32 v19, v34
	v_mov_b32_e32 v64, v39
	v_mov_b32_e32 v65, v43
	v_pk_mul_f32 v[24:25], v[24:25], v[24:25]
	v_mov_b32_e32 v62, v38
	v_mov_b32_e32 v63, v42
	v_mov_b32_e32 v66, v22
	v_mov_b32_e32 v67, v36
	v_pk_mul_f32 v[64:65], v[64:65], v[64:65]
	v_pk_fma_f32 v[18:19], v[18:19], v[18:19], v[24:25]
	v_mov_b32_e32 v68, v40
	v_mov_b32_e32 v69, v44
	v_mov_b32_e32 v70, v23
	v_mov_b32_e32 v71, v37
	v_pk_fma_f32 v[24:25], v[62:63], v[62:63], v[64:65]
	v_pk_fma_f32 v[18:19], v[66:67], v[66:67], v[18:19]
	v_mov_b32_e32 v72, v41
	v_mov_b32_e32 v73, v45
	v_pk_fma_f32 v[24:25], v[68:69], v[68:69], v[24:25]
	v_pk_fma_f32 v[18:19], v[70:71], v[70:71], v[18:19]
	v_pk_fma_f32 v[24:25], v[72:73], v[72:73], v[24:25]
	v_add_f32_e32 v3, v18, v19
	v_add_f32_e32 v3, v3, v24
	v_add_f32_e32 v3, v3, v25
	ds_bpermute_b32 v5, v27, v3
	v_ashrrev_i32_e32 v18, 8, v26
	v_lshlrev_b32_e32 v24, 1, v11
	v_ashrrev_i32_e32 v19, 31, v18
	v_lshlrev_b64 v[18:19], 19, v[18:19]
	s_waitcnt lgkmcnt(0)
	v_add_f32_e32 v3, v3, v5
	ds_bpermute_b32 v5, v28, v3
	v_mov_b32_e32 v25, v145
	v_lshl_add_u64 v[18:19], s[8:9], 0, v[18:19]
	v_lshl_add_u64 v[18:19], v[18:19], 0, v[24:25]
	v_pk_add_f32 v[24:25], v[46:47], 1.0 op_sel_hi:[1,0]
	s_waitcnt lgkmcnt(0)
	v_add_f32_e32 v3, v3, v5
	ds_bpermute_b32 v5, v29, v3
	v_pk_add_f32 v[46:47], v[48:49], 1.0 op_sel_hi:[1,0]
	v_add_u32_e32 v26, s14, v26
	s_waitcnt lgkmcnt(0)
	v_add_f32_e32 v7, v3, v5
	ds_bpermute_b32 v9, v30, v7
	v_mov_b32_e32 v3, v145
	v_lshl_add_u64 v[64:65], v[18:19], 0, v[2:3]
	v_mov_b32_e32 v5, v145
	v_lshl_add_u64 v[18:19], v[64:65], 0, v[4:5]
	s_waitcnt lgkmcnt(0)
	v_add_f32_e32 v9, v7, v9
	ds_bpermute_b32 v13, v31, v9
	v_mov_b32_e32 v7, v145
	v_lshl_add_u64 v[62:63], v[58:59], 0, v[6:7]
	s_waitcnt lgkmcnt(0)
	v_add_f32_e32 v9, v9, v13
	ds_bpermute_b32 v11, v32, v9
	v_mov_b32_e32 v13, v145
	s_waitcnt lgkmcnt(0)
	v_add_f32_e32 v3, v9, v11
	v_fmamk_f32 v3, v3, 0x3a800000, v169
	v_mul_f32_e32 v7, 0x4b800000, v3
	v_cmp_gt_f32_e32 vcc, s77, v3
	v_mov_b32_e32 v9, v145
	v_mov_b32_e32 v11, v145
	v_cndmask_b32_e32 v3, v3, v7, vcc
	v_rsq_f32_e32 v3, v3
	s_nop 0
	v_mul_f32_e32 v5, 0x45800000, v3
	v_cndmask_b32_e32 v66, v3, v5, vcc
	v_pk_mul_f32 v[20:21], v[20:21], v[66:67] op_sel_hi:[1,0]
	v_pk_mul_f32 v[22:23], v[22:23], v[66:67] op_sel_hi:[1,0]
	v_pk_mul_f32 v[20:21], v[50:51], v[20:21]
	v_pk_mul_f32 v[22:23], v[52:53], v[22:23]
	v_pk_fma_f32 v[20:21], v[24:25], v[20:21], v[54:55]
	v_pk_fma_f32 v[22:23], v[46:47], v[22:23], v[56:57]
	v_cvt_pk_bf16_f32 v20, v20, v21
	v_cvt_pk_bf16_f32 v21, v22, v23
	global_store_dwordx2 v[18:19], v[20:21], off
	v_pk_mul_f32 v[34:35], v[34:35], v[66:67] op_sel_hi:[1,0]
	v_pk_mul_f32 v[36:37], v[36:37], v[66:67] op_sel_hi:[1,0]
	v_lshl_add_u64 v[52:53], v[64:65], 0, v[8:9]
	v_lshl_add_u64 v[50:51], v[58:59], 0, v[10:11]
	v_pk_mul_f32 v[38:39], v[38:39], v[66:67] op_sel_hi:[1,0]
	v_pk_mul_f32 v[40:41], v[40:41], v[66:67] op_sel_hi:[1,0]
	v_cmp_lt_i32_e32 vcc, s12, v26
	s_or_b64 s[10:11], vcc, s[10:11]
	v_pk_mul_f32 v[18:19], v[34:35], v[74:75]
	v_pk_add_f32 v[22:23], v[78:79], 1.0 op_sel_hi:[1,0]
	v_pk_mul_f32 v[20:21], v[36:37], v[76:77]
	v_pk_add_f32 v[24:25], v[80:81], 1.0 op_sel_hi:[1,0]
	v_pk_fma_f32 v[18:19], v[18:19], v[22:23], v[82:83]
	v_pk_fma_f32 v[20:21], v[20:21], v[24:25], v[84:85]
	v_cvt_pk_bf16_f32 v18, v18, v19
	v_cvt_pk_bf16_f32 v19, v20, v21
	global_store_dwordx2 v[52:53], v[18:19], off
	v_lshl_add_u64 v[48:49], v[64:65], 0, v[12:13]
	v_lshl_add_u64 v[46:47], v[58:59], 0, v[14:15]
	v_pk_mul_f32 v[18:19], v[38:39], v[86:87]
	v_pk_add_f32 v[22:23], v[90:91], 1.0 op_sel_hi:[1,0]
	v_pk_mul_f32 v[20:21], v[40:41], v[88:89]
	v_pk_add_f32 v[24:25], v[92:93], 1.0 op_sel_hi:[1,0]
	v_pk_fma_f32 v[18:19], v[18:19], v[22:23], v[94:95]
	v_pk_fma_f32 v[20:21], v[20:21], v[24:25], v[96:97]
	v_cvt_pk_bf16_f32 v18, v18, v19
	v_cvt_pk_bf16_f32 v19, v20, v21
	global_store_dwordx2 v[48:49], v[18:19], off
	v_pk_mul_f32 v[40:41], v[42:43], v[66:67] op_sel_hi:[1,0]
	v_pk_mul_f32 v[42:43], v[44:45], v[66:67] op_sel_hi:[1,0]
	v_lshl_add_u64 v[38:39], v[64:65], 0, v[16:17]
	v_pk_mul_f32 v[18:19], v[40:41], v[98:99]
	v_pk_add_f32 v[22:23], v[102:103], 1.0 op_sel_hi:[1,0]
	v_pk_mul_f32 v[20:21], v[42:43], v[100:101]
	v_pk_add_f32 v[24:25], v[104:105], 1.0 op_sel_hi:[1,0]
	v_pk_fma_f32 v[18:19], v[18:19], v[22:23], v[106:107]
	v_pk_fma_f32 v[20:21], v[20:21], v[24:25], v[108:109]
	v_cvt_pk_bf16_f32 v18, v18, v19
	v_cvt_pk_bf16_f32 v19, v20, v21
	global_store_dwordx2 v[38:39], v[18:19], off
	s_andn2_b64 exec, exec, s[10:11]
	s_cbranch_execz .LBB0_500
